# GEMM K-loop: one static priority raise for waves 4-7 at loop entry instead of per-segment s_setprio flips
# baseline (speedup 1.0000x reference)
; #define PG8_STAGE(bufoff, gbase, voff) do { _Pragma("unroll") for (int _i = 0; _i < 2; ++_i) \
;         __builtin_amdgcn_global_load_lds((const unsigned*)((const char*)(gbase) + (voff)[_i]), (PG8_LAS unsigned*)(lds + (bufoff) + ldsw + _i * 8192), 16, 0, 0); } while (0)
; #define PG8_LDA(dst, b, h) do { _Pragma("unroll") for (int m = 0; m < 4; ++m) _Pragma("unroll") for (int k = 0; k < 2; ++k) dst[m][k] = *(const PG8_LAS bf16x8*)(lds + PG8_SA(b, h) + aoff + m * 2048 + k * 1024); } while (0)
; #define PG8_LDB(dst, b, h) do { _Pragma("unroll") for (int n = 0; n < 2; ++n) _Pragma("unroll") for (int k = 0; k < 2; ++k) dst[n][k] = *(const PG8_LAS bf16x8*)(lds + PG8_SB(b, h) + boff + n * 2048 + k * 1024); } while (0)
; #define PG8_WAIT_V(n) asm volatile("s_waitcnt vmcnt(" #n ")" ::: "memory")
; #define PG8_WAIT_L(n) asm volatile("s_waitcnt lgkmcnt(" #n ")" ::: "memory")
; #define PG8_BAR __builtin_amdgcn_s_barrier()
; template <class Epi, class Sched, bool ALIGN_EPI = false, bool SP2 = false>
; __device__ __forceinline__ void gemm_phase(PG8_LAS unsigned char* lds, const Gemm g, const Sched& S, const Epi& E) {
;     ...
;     for (;;) {
;         const bool has_next = S.next(ui + 1, nxt);
;         const char* nA = has_next ? (const char*)g.A + (size_t)nxt.pm * tstep + (size_t)(nxt.ko / BK) * kstep : cA; const char* nB = has_next ? (const char*)g.Bt + (size_t)nxt.pn * tstep + (size_t)(nxt.ko / BK) * kstep : cB;
;         for (int t = 0; t < nt; t += 2) {
;             const bool last = (t == nt - 2);
;             const char* a1 = cA + (size_t)(t + 1) * kstep;
;             const char* a2 = last ? nA : cA + (size_t)(t + 2) * kstep; const char* b2 = last ? nB : cB + (size_t)(t + 2) * kstep;
;             const char* a3 = a2 + kstep; const char* b3 = b2 + kstep;
;             if (last && has_next) S.a_ready(nxt);
;             if constexpr (SP2) {
;             PG8_LDB(B0, 0, 0); PG8_LDB(B1, 0, 1); PG8_SCHED; PG8_LDA(At, 0, 0); PG8_STAGE(PG8_SA(1, 1), a1 + hstep, voffA);
;             PG8_WAIT_V(8); PG8_WAIT_L(0); PG8_BAR; PG8_MMA(0, 0, At, B0); PG8_MMA(0, 1, At, B1); PG8_BAR; PG8_SCHED;
;     ...
; #pragma unroll
;         for (int a = 0; a < 2; ++a)
; #pragma unroll
;             for (int b = 0; b < 2; ++b)
; #pragma unroll
;                 for (int m = 0; m < 4; ++m)
; #pragma unroll
;                     for (int n = 0; n < 2; ++n) acc[a][b][m][n] = (f32x4){0.f, 0.f, 0.f, 0.f};
.LBB0_161:
	s_add_u32 s25, s10, s21
	v_mov_b32_e32 v0, 0
	s_addc_u32 s26, s11, 0
	s_mov_b64 s[12:13], 0
	v_mov_b32_e32 v1, v0
	v_mov_b32_e32 v2, v0
	v_mov_b32_e32 v3, v0
	v_mov_b32_e32 v8, v0
	v_mov_b32_e32 v9, v0
	v_mov_b32_e32 v10, v0
	v_mov_b32_e32 v11, v0
	v_mov_b32_e32 v16, v0
	v_mov_b32_e32 v17, v0
	v_mov_b32_e32 v18, v0
	v_mov_b32_e32 v19, v0
	v_mov_b32_e32 v24, v0
	v_mov_b32_e32 v25, v0
	v_mov_b32_e32 v26, v0
	v_mov_b32_e32 v27, v0
	v_mov_b32_e32 v32, v0
	v_mov_b32_e32 v33, v0
	v_mov_b32_e32 v34, v0
	v_mov_b32_e32 v35, v0
	v_mov_b32_e32 v40, v0
	v_mov_b32_e32 v41, v0
	v_mov_b32_e32 v42, v0
	v_mov_b32_e32 v43, v0
	v_mov_b32_e32 v48, v0
	v_mov_b32_e32 v49, v0
	v_mov_b32_e32 v50, v0
	v_mov_b32_e32 v51, v0
	v_mov_b32_e32 v56, v0
	v_mov_b32_e32 v57, v0
	v_mov_b32_e32 v58, v0
	v_mov_b32_e32 v59, v0
	v_mov_b32_e32 v4, v0
	v_mov_b32_e32 v5, v0
	v_mov_b32_e32 v6, v0
	v_mov_b32_e32 v7, v0
	v_mov_b32_e32 v12, v0
	v_mov_b32_e32 v13, v0
	v_mov_b32_e32 v14, v0
	v_mov_b32_e32 v15, v0
	v_mov_b32_e32 v20, v0
	v_mov_b32_e32 v21, v0
	v_mov_b32_e32 v22, v0
	v_mov_b32_e32 v23, v0
	v_mov_b32_e32 v28, v0
	v_mov_b32_e32 v29, v0
	v_mov_b32_e32 v30, v0
	v_mov_b32_e32 v31, v0
	v_mov_b32_e32 v36, v0
	v_mov_b32_e32 v37, v0
	v_mov_b32_e32 v38, v0
	v_mov_b32_e32 v39, v0
	v_mov_b32_e32 v44, v0
	v_mov_b32_e32 v45, v0
	v_mov_b32_e32 v46, v0
	v_mov_b32_e32 v47, v0
	v_mov_b32_e32 v52, v0
	v_mov_b32_e32 v53, v0
	v_mov_b32_e32 v54, v0
	v_mov_b32_e32 v55, v0
	v_mov_b32_e32 v60, v0
	v_mov_b32_e32 v61, v0
	v_mov_b32_e32 v62, v0
	v_mov_b32_e32 v63, v0
	v_mov_b32_e32 v64, v0
	v_mov_b32_e32 v65, v0
	v_mov_b32_e32 v66, v0
	v_mov_b32_e32 v67, v0
	v_mov_b32_e32 v72, v0
	v_mov_b32_e32 v73, v0
	v_mov_b32_e32 v74, v0
	v_mov_b32_e32 v75, v0
	v_mov_b32_e32 v80, v0
	v_mov_b32_e32 v81, v0
	v_mov_b32_e32 v82, v0
	v_mov_b32_e32 v83, v0
	v_mov_b32_e32 v88, v0
	v_mov_b32_e32 v89, v0
	v_mov_b32_e32 v90, v0
	v_mov_b32_e32 v91, v0
	v_mov_b32_e32 v96, v0
	v_mov_b32_e32 v97, v0
	v_mov_b32_e32 v98, v0
	v_mov_b32_e32 v99, v0
	v_mov_b32_e32 v104, v0
	v_mov_b32_e32 v105, v0
	v_mov_b32_e32 v106, v0
	v_mov_b32_e32 v107, v0
	s_waitcnt vmcnt(0)
	v_mov_b32_e32 v112, v0
	v_mov_b32_e32 v113, v0
	v_mov_b32_e32 v114, v0
	v_mov_b32_e32 v115, v0
	v_mov_b32_e32 v120, v0
	v_mov_b32_e32 v121, v0
	v_mov_b32_e32 v122, v0
	v_mov_b32_e32 v123, v0
	v_mov_b32_e32 v68, v0
	v_mov_b32_e32 v69, v0
	v_mov_b32_e32 v70, v0
	v_mov_b32_e32 v71, v0
	v_mov_b32_e32 v76, v0
	v_mov_b32_e32 v77, v0
	v_mov_b32_e32 v78, v0
	v_mov_b32_e32 v79, v0
	v_mov_b32_e32 v84, v0
	v_mov_b32_e32 v85, v0
	v_mov_b32_e32 v86, v0
	v_mov_b32_e32 v87, v0
	v_mov_b32_e32 v92, v0
	v_mov_b32_e32 v93, v0
	v_mov_b32_e32 v94, v0
	v_mov_b32_e32 v95, v0
	v_mov_b32_e32 v100, v0
	v_mov_b32_e32 v101, v0
	v_mov_b32_e32 v102, v0
	v_mov_b32_e32 v103, v0
	v_mov_b32_e32 v108, v0
	v_mov_b32_e32 v109, v0
	v_mov_b32_e32 v110, v0
	v_mov_b32_e32 v111, v0
	v_mov_b32_e32 v116, v0
	v_mov_b32_e32 v117, v0
	v_mov_b32_e32 v118, v0
	v_mov_b32_e32 v119, v0
	v_mov_b32_e32 v124, v0
	v_mov_b32_e32 v125, v0
	v_mov_b32_e32 v126, v0
	v_mov_b32_e32 v127, v0
	s_and_b64 vcc, exec, s[86:87]
	s_cbranch_vccnz .Lsp_skip
	s_setprio 1
.Lsp_skip:
.LBB0_162:
	s_add_u32 s94, s12, 1
	s_addc_u32 s95, s13, 0
	s_add_u32 s14, s12, 2
	s_addc_u32 s15, s13, 0
	s_lshl_b64 s[30:31], s[14:15], s60
	s_add_u32 s13, s10, s30
	s_addc_u32 s29, s11, s31
	s_add_u32 s30, s8, s30
	s_addc_u32 s31, s9, s31
	s_cmp_eq_u32 s2, s12
	s_cselect_b32 s92, s88, s13
	s_cselect_b32 s93, s89, s29
	s_cselect_b32 s30, s90, s30
	s_cselect_b32 s31, s91, s31
	s_add_u32 s12, s92, s20
	s_addc_u32 s13, s93, 0
	s_add_i32 s29, 0, 0x10000
	s_add_i32 s50, 0, 0x14000
	v_add_u32_e32 v140, s29, v231
	v_add_u32_e32 v156, s50, v231
	ds_read_b128 v[128:131], v140
	ds_read_b128 v[132:135], v140 offset:1024
	ds_read_b128 v[136:139], v140 offset:2048
	ds_read_b128 v[140:143], v140 offset:3072
	ds_read_b128 v[144:147], v156
	ds_read_b128 v[148:151], v156 offset:1024
	ds_read_b128 v[152:155], v156 offset:2048
	ds_read_b128 v[156:159], v156 offset:3072
	s_lshl_b64 s[94:95], s[94:95], s60
	s_add_u32 s94, s25, s94
	s_addc_u32 s95, s26, s95
	v_lshl_add_u64 v[214:215], s[94:95], 0, v[174:175]
	s_add_i32 m0, s18, 0xc000
	ds_read_b128 v[160:163], v233
	ds_read_b128 v[210:213], v233 offset:1024
	ds_read_b128 v[234:237], v233 offset:2048
	ds_read_b128 v[238:241], v233 offset:3072
	ds_read_b128 v[242:245], v233 offset:4096
	ds_read_b128 v[246:249], v233 offset:5120
	ds_read_b128 v[250:253], v233 offset:6144
	ds_read_b128 v[218:221], v233 offset:7168
	global_load_lds_dwordx4 v[214:215], off
	v_lshl_add_u64 v[214:215], s[94:95], 0, v[176:177]
	s_add_i32 m0, s18, 0xe000
	s_nop 0
	global_load_lds_dwordx4 v[214:215], off
	s_waitcnt vmcnt(8)
	s_waitcnt lgkmcnt(0)
	s_barrier
; #define PG8_STAGE(bufoff, gbase, voff) do { _Pragma("unroll") for (int _i = 0; _i < 2; ++_i) \
;         __builtin_amdgcn_global_load_lds((const unsigned*)((const char*)(gbase) + (voff)[_i]), (PG8_LAS unsigned*)(lds + (bufoff) + ldsw + _i * 8192), 16, 0, 0); } while (0)
; #define PG8_LDA(dst, b, h) do { _Pragma("unroll") for (int m = 0; m < 4; ++m) _Pragma("unroll") for (int k = 0; k < 2; ++k) dst[m][k] = *(const PG8_LAS bf16x8*)(lds + PG8_SA(b, h) + aoff + m * 2048 + k * 1024); } while (0)
; #define PG8_MMA(ai, bj, At, Bt) do { __builtin_amdgcn_s_setprio(1); _Pragma("unroll") for (int m = 0; m < 4; ++m) _Pragma("unroll") for (int n = 0; n < 2; ++n) _Pragma("unroll") for (int k = 0; k < 2; ++k) \
;         acc[ai][bj][m][n] = __builtin_amdgcn_mfma_f32_16x16x32_bf16(Bt[n][k], At[m][k], acc[ai][bj][m][n], 0, 0, 0); __builtin_amdgcn_s_setprio(0); } while (0)
; #define PG8_WAIT_V(n) asm volatile("s_waitcnt vmcnt(" #n ")" ::: "memory")
; #define PG8_WAIT_L(n) asm volatile("s_waitcnt lgkmcnt(" #n ")" ::: "memory")
; #define PG8_BAR __builtin_amdgcn_s_barrier()
; #define PG8_SCHED __builtin_amdgcn_sched_barrier(0)
; template <class Epi, class Sched, bool ALIGN_EPI = false, bool SP2 = false>
; __device__ __forceinline__ void gemm_phase(PG8_LAS unsigned char* lds, const Gemm g, const Sched& S, const Epi& E) {
;     ...
;             PG8_WAIT_V(8); PG8_WAIT_L(0); PG8_BAR; PG8_MMA(0, 0, At, B0); PG8_MMA(0, 1, At, B1); PG8_BAR; PG8_SCHED;
;             PG8_LDA(At, 0, 1); PG8_STAGE(PG8_SB(0, 0), b2, voffB); PG8_STAGE(PG8_SB(0, 1), b2 + hstep, voffB); PG8_STAGE(PG8_SA(0, 0), a2, voffA);
;             PG8_WAIT_V(8); PG8_WAIT_L(0); PG8_BAR; PG8_MMA(1, 0, At, B0); PG8_MMA(1, 1, At, B1); PG8_BAR; PG8_SCHED;
	v_mfma_f32_16x16x32_bf16 v[124:127], v[128:131], v[160:163], v[124:127]
	v_mfma_f32_16x16x32_bf16 v[116:119], v[136:139], v[160:163], v[116:119]
	v_mfma_f32_16x16x32_bf16 v[108:111], v[128:131], v[234:237], v[108:111]
	v_mfma_f32_16x16x32_bf16 v[100:103], v[136:139], v[234:237], v[100:103]
	v_mfma_f32_16x16x32_bf16 v[92:95], v[128:131], v[242:245], v[92:95]
	v_mfma_f32_16x16x32_bf16 v[84:87], v[136:139], v[242:245], v[84:87]
	v_mfma_f32_16x16x32_bf16 v[76:79], v[128:131], v[250:253], v[76:79]
	v_mfma_f32_16x16x32_bf16 v[68:71], v[136:139], v[250:253], v[68:71]
	v_mfma_f32_16x16x32_bf16 v[124:127], v[132:135], v[210:213], v[124:127]
	v_mfma_f32_16x16x32_bf16 v[116:119], v[140:143], v[210:213], v[116:119]
	v_mfma_f32_16x16x32_bf16 v[108:111], v[132:135], v[238:241], v[108:111]
	v_mfma_f32_16x16x32_bf16 v[100:103], v[140:143], v[238:241], v[100:103]
	v_mfma_f32_16x16x32_bf16 v[92:95], v[132:135], v[246:249], v[92:95]
	v_mfma_f32_16x16x32_bf16 v[84:87], v[140:143], v[246:249], v[84:87]
	v_mfma_f32_16x16x32_bf16 v[76:79], v[132:135], v[218:221], v[76:79]
	v_mfma_f32_16x16x32_bf16 v[68:71], v[140:143], v[218:221], v[68:71]
	v_mfma_f32_16x16x32_bf16 v[120:123], v[144:147], v[160:163], v[120:123]
	v_mfma_f32_16x16x32_bf16 v[112:115], v[152:155], v[160:163], v[112:115]
	v_mfma_f32_16x16x32_bf16 v[104:107], v[144:147], v[234:237], v[104:107]
	v_mfma_f32_16x16x32_bf16 v[96:99], v[152:155], v[234:237], v[96:99]
	v_mfma_f32_16x16x32_bf16 v[88:91], v[144:147], v[242:245], v[88:91]
	v_mfma_f32_16x16x32_bf16 v[80:83], v[152:155], v[242:245], v[80:83]
	v_mfma_f32_16x16x32_bf16 v[72:75], v[144:147], v[250:253], v[72:75]
	v_mfma_f32_16x16x32_bf16 v[64:67], v[152:155], v[250:253], v[64:67]
	v_mfma_f32_16x16x32_bf16 v[120:123], v[148:151], v[210:213], v[120:123]
	v_mfma_f32_16x16x32_bf16 v[112:115], v[156:159], v[210:213], v[112:115]
	v_mfma_f32_16x16x32_bf16 v[104:107], v[148:151], v[238:241], v[104:107]
	v_mfma_f32_16x16x32_bf16 v[96:99], v[156:159], v[238:241], v[96:99]
	v_mfma_f32_16x16x32_bf16 v[88:91], v[148:151], v[246:249], v[88:91]
	v_mfma_f32_16x16x32_bf16 v[80:83], v[156:159], v[246:249], v[80:83]
	v_mfma_f32_16x16x32_bf16 v[72:75], v[148:151], v[218:221], v[72:75]
	v_mfma_f32_16x16x32_bf16 v[64:67], v[156:159], v[218:221], v[64:67]
	s_barrier
	s_add_i32 s29, s29, s77
	v_lshl_add_u64 v[214:215], s[30:31], 0, v[174:175]
	s_mov_b32 m0, s29
	ds_read_b128 v[160:163], v233 offset:16384
	ds_read_b128 v[210:213], v233 offset:17408
	ds_read_b128 v[218:221], v233 offset:18432
	ds_read_b128 v[234:237], v233 offset:19456
	ds_read_b128 v[238:241], v233 offset:20480
	ds_read_b128 v[242:245], v233 offset:21504
	ds_read_b128 v[246:249], v233 offset:22528
	ds_read_b128 v[250:253], v233 offset:23552
	global_load_lds_dwordx4 v[214:215], off
	s_add_i32 m0, s29, 0x2000
	s_add_u32 s94, s30, s21
	v_lshl_add_u64 v[214:215], s[30:31], 0, v[176:177]
	s_addc_u32 s95, s31, 0
	s_add_i32 s29, s50, s77
	global_load_lds_dwordx4 v[214:215], off
	v_lshl_add_u64 v[214:215], s[94:95], 0, v[174:175]
	s_mov_b32 m0, s29
	s_nop 0
	global_load_lds_dwordx4 v[214:215], off
	v_lshl_add_u64 v[214:215], s[94:95], 0, v[176:177]
	s_add_i32 m0, s29, 0x2000
	s_nop 0
	global_load_lds_dwordx4 v[214:215], off
	v_lshl_add_u64 v[214:215], s[92:93], 0, v[174:175]
	s_mov_b32 m0, s18
	s_nop 0
	global_load_lds_dwordx4 v[214:215], off
	v_lshl_add_u64 v[214:215], s[92:93], 0, v[176:177]
	s_mov_b32 m0, s19
	s_nop 0
	global_load_lds_dwordx4 v[214:215], off
	s_waitcnt vmcnt(8)
	s_waitcnt lgkmcnt(0)
	s_barrier
	v_mfma_f32_16x16x32_bf16 v[60:63], v[128:131], v[160:163], v[60:63]
	v_mfma_f32_16x16x32_bf16 v[52:55], v[136:139], v[160:163], v[52:55]
	v_mfma_f32_16x16x32_bf16 v[44:47], v[128:131], v[218:221], v[44:47]
	v_mfma_f32_16x16x32_bf16 v[36:39], v[136:139], v[218:221], v[36:39]
	v_mfma_f32_16x16x32_bf16 v[28:31], v[128:131], v[238:241], v[28:31]
	v_mfma_f32_16x16x32_bf16 v[20:23], v[136:139], v[238:241], v[20:23]
	v_mfma_f32_16x16x32_bf16 v[12:15], v[128:131], v[246:249], v[12:15]
	v_mfma_f32_16x16x32_bf16 v[4:7], v[136:139], v[246:249], v[4:7]
	v_mfma_f32_16x16x32_bf16 v[60:63], v[132:135], v[210:213], v[60:63]
	v_mfma_f32_16x16x32_bf16 v[52:55], v[140:143], v[210:213], v[52:55]
	v_mfma_f32_16x16x32_bf16 v[44:47], v[132:135], v[234:237], v[44:47]
	v_mfma_f32_16x16x32_bf16 v[36:39], v[140:143], v[234:237], v[36:39]
	v_mfma_f32_16x16x32_bf16 v[28:31], v[132:135], v[242:245], v[28:31]
	v_mfma_f32_16x16x32_bf16 v[20:23], v[140:143], v[242:245], v[20:23]
	v_mfma_f32_16x16x32_bf16 v[12:15], v[132:135], v[250:253], v[12:15]
	v_mfma_f32_16x16x32_bf16 v[4:7], v[140:143], v[250:253], v[4:7]
	v_mfma_f32_16x16x32_bf16 v[56:59], v[144:147], v[160:163], v[56:59]
	v_mfma_f32_16x16x32_bf16 v[48:51], v[152:155], v[160:163], v[48:51]
	v_mfma_f32_16x16x32_bf16 v[40:43], v[144:147], v[218:221], v[40:43]
	v_mfma_f32_16x16x32_bf16 v[32:35], v[152:155], v[218:221], v[32:35]
	v_mfma_f32_16x16x32_bf16 v[24:27], v[144:147], v[238:241], v[24:27]
	v_mfma_f32_16x16x32_bf16 v[16:19], v[152:155], v[238:241], v[16:19]
	v_mfma_f32_16x16x32_bf16 v[8:11], v[144:147], v[246:249], v[8:11]
	v_mfma_f32_16x16x32_bf16 v[0:3], v[152:155], v[246:249], v[0:3]
	v_mfma_f32_16x16x32_bf16 v[56:59], v[148:151], v[210:213], v[56:59]
	v_mfma_f32_16x16x32_bf16 v[48:51], v[156:159], v[210:213], v[48:51]
	v_mfma_f32_16x16x32_bf16 v[40:43], v[148:151], v[234:237], v[40:43]
	v_mfma_f32_16x16x32_bf16 v[32:35], v[156:159], v[234:237], v[32:35]
	v_mfma_f32_16x16x32_bf16 v[24:27], v[148:151], v[242:245], v[24:27]
	v_mfma_f32_16x16x32_bf16 v[16:19], v[156:159], v[242:245], v[16:19]
	v_mfma_f32_16x16x32_bf16 v[8:11], v[148:151], v[250:253], v[8:11]
	v_mfma_f32_16x16x32_bf16 v[0:3], v[156:159], v[250:253], v[0:3]
	s_barrier
; #define PG8_STAGE(bufoff, gbase, voff) do { _Pragma("unroll") for (int _i = 0; _i < 2; ++_i) \
;         __builtin_amdgcn_global_load_lds((const unsigned*)((const char*)(gbase) + (voff)[_i]), (PG8_LAS unsigned*)(lds + (bufoff) + ldsw + _i * 8192), 16, 0, 0); } while (0)
; #define PG8_LDA(dst, b, h) do { _Pragma("unroll") for (int m = 0; m < 4; ++m) _Pragma("unroll") for (int k = 0; k < 2; ++k) dst[m][k] = *(const PG8_LAS bf16x8*)(lds + PG8_SA(b, h) + aoff + m * 2048 + k * 1024); } while (0)
; #define PG8_LDB(dst, b, h) do { _Pragma("unroll") for (int n = 0; n < 2; ++n) _Pragma("unroll") for (int k = 0; k < 2; ++k) dst[n][k] = *(const PG8_LAS bf16x8*)(lds + PG8_SB(b, h) + boff + n * 2048 + k * 1024); } while (0)
; #define PG8_MMA(ai, bj, At, Bt) do { __builtin_amdgcn_s_setprio(1); _Pragma("unroll") for (int m = 0; m < 4; ++m) _Pragma("unroll") for (int n = 0; n < 2; ++n) _Pragma("unroll") for (int k = 0; k < 2; ++k) \
;         acc[ai][bj][m][n] = __builtin_amdgcn_mfma_f32_16x16x32_bf16(Bt[n][k], At[m][k], acc[ai][bj][m][n], 0, 0, 0); __builtin_amdgcn_s_setprio(0); } while (0)
; #define PG8_WAIT_V(n) asm volatile("s_waitcnt vmcnt(" #n ")" ::: "memory")
; #define PG8_WAIT_L(n) asm volatile("s_waitcnt lgkmcnt(" #n ")" ::: "memory")
; #define PG8_BAR __builtin_amdgcn_s_barrier()
; #define PG8_SCHED __builtin_amdgcn_sched_barrier(0)
; template <class Epi, class Sched, bool ALIGN_EPI = false, bool SP2 = false>
; __device__ __forceinline__ void gemm_phase(PG8_LAS unsigned char* lds, const Gemm g, const Sched& S, const Epi& E) {
;     ...
;             PG8_LDB(B0, 1, 0); PG8_LDB(B1, 1, 1); PG8_SCHED; PG8_LDA(At, 1, 0); PG8_STAGE(PG8_SA(0, 1), a2 + hstep, voffA);
;             PG8_WAIT_V(8); PG8_WAIT_L(0); PG8_BAR; PG8_MMA(0, 0, At, B0); PG8_MMA(0, 1, At, B1); PG8_BAR; PG8_SCHED;
	s_add_i32 s29, 0, 0x18000
	s_add_i32 s50, 0, 0x1c000
	v_add_u32_e32 v140, s29, v231
	v_add_u32_e32 v156, s50, v231
	ds_read_b128 v[128:131], v140
	ds_read_b128 v[132:135], v140 offset:1024
	ds_read_b128 v[136:139], v140 offset:2048
	ds_read_b128 v[140:143], v140 offset:3072
	ds_read_b128 v[144:147], v156
	ds_read_b128 v[148:151], v156 offset:1024
	ds_read_b128 v[152:155], v156 offset:2048
	ds_read_b128 v[156:159], v156 offset:3072
	s_add_u32 s92, s92, s21
	s_addc_u32 s93, s93, 0
	s_mov_b32 m0, s45
	v_lshl_add_u64 v[214:215], s[92:93], 0, v[174:175]
	ds_read_b128 v[160:163], v233 offset:32768
	ds_read_b128 v[210:213], v233 offset:33792
	ds_read_b128 v[218:221], v233 offset:34816
	ds_read_b128 v[234:237], v233 offset:35840
	ds_read_b128 v[238:241], v233 offset:36864
	ds_read_b128 v[242:245], v233 offset:37888
	ds_read_b128 v[246:249], v233 offset:38912
	ds_read_b128 v[250:253], v233 offset:39936
	global_load_lds_dwordx4 v[214:215], off
	v_lshl_add_u64 v[214:215], s[92:93], 0, v[176:177]
	s_mov_b32 m0, s57
	s_nop 0
	global_load_lds_dwordx4 v[214:215], off
	s_waitcnt vmcnt(8)
	s_waitcnt lgkmcnt(0)
	s_barrier
	v_mfma_f32_16x16x32_bf16 v[124:127], v[128:131], v[160:163], v[124:127]
	v_mfma_f32_16x16x32_bf16 v[116:119], v[136:139], v[160:163], v[116:119]
	v_mfma_f32_16x16x32_bf16 v[108:111], v[128:131], v[218:221], v[108:111]
	v_mfma_f32_16x16x32_bf16 v[100:103], v[136:139], v[218:221], v[100:103]
	v_mfma_f32_16x16x32_bf16 v[92:95], v[128:131], v[238:241], v[92:95]
	v_mfma_f32_16x16x32_bf16 v[84:87], v[136:139], v[238:241], v[84:87]
	v_mfma_f32_16x16x32_bf16 v[76:79], v[128:131], v[246:249], v[76:79]
	v_mfma_f32_16x16x32_bf16 v[68:71], v[136:139], v[246:249], v[68:71]
	v_mfma_f32_16x16x32_bf16 v[124:127], v[132:135], v[210:213], v[124:127]
	v_mfma_f32_16x16x32_bf16 v[116:119], v[140:143], v[210:213], v[116:119]
	v_mfma_f32_16x16x32_bf16 v[108:111], v[132:135], v[234:237], v[108:111]
	v_mfma_f32_16x16x32_bf16 v[100:103], v[140:143], v[234:237], v[100:103]
	v_mfma_f32_16x16x32_bf16 v[92:95], v[132:135], v[242:245], v[92:95]
	v_mfma_f32_16x16x32_bf16 v[84:87], v[140:143], v[242:245], v[84:87]
	v_mfma_f32_16x16x32_bf16 v[76:79], v[132:135], v[250:253], v[76:79]
	v_mfma_f32_16x16x32_bf16 v[68:71], v[140:143], v[250:253], v[68:71]
	v_mfma_f32_16x16x32_bf16 v[120:123], v[144:147], v[160:163], v[120:123]
	v_mfma_f32_16x16x32_bf16 v[112:115], v[152:155], v[160:163], v[112:115]
	v_mfma_f32_16x16x32_bf16 v[104:107], v[144:147], v[218:221], v[104:107]
	v_mfma_f32_16x16x32_bf16 v[96:99], v[152:155], v[218:221], v[96:99]
	v_mfma_f32_16x16x32_bf16 v[88:91], v[144:147], v[238:241], v[88:91]
	v_mfma_f32_16x16x32_bf16 v[80:83], v[152:155], v[238:241], v[80:83]
	v_mfma_f32_16x16x32_bf16 v[72:75], v[144:147], v[246:249], v[72:75]
	v_mfma_f32_16x16x32_bf16 v[64:67], v[152:155], v[246:249], v[64:67]
	v_mfma_f32_16x16x32_bf16 v[120:123], v[148:151], v[210:213], v[120:123]
	v_mfma_f32_16x16x32_bf16 v[112:115], v[156:159], v[210:213], v[112:115]
	v_mfma_f32_16x16x32_bf16 v[104:107], v[148:151], v[234:237], v[104:107]
	v_mfma_f32_16x16x32_bf16 v[96:99], v[156:159], v[234:237], v[96:99]
	v_mfma_f32_16x16x32_bf16 v[88:91], v[148:151], v[242:245], v[88:91]
	v_mfma_f32_16x16x32_bf16 v[80:83], v[156:159], v[242:245], v[80:83]
	v_mfma_f32_16x16x32_bf16 v[72:75], v[148:151], v[250:253], v[72:75]
	v_mfma_f32_16x16x32_bf16 v[64:67], v[156:159], v[250:253], v[64:67]
	s_barrier
; #define PG8_STAGE(bufoff, gbase, voff) do { _Pragma("unroll") for (int _i = 0; _i < 2; ++_i) \
;         __builtin_amdgcn_global_load_lds((const unsigned*)((const char*)(gbase) + (voff)[_i]), (PG8_LAS unsigned*)(lds + (bufoff) + ldsw + _i * 8192), 16, 0, 0); } while (0)
; #define PG8_LDA(dst, b, h) do { _Pragma("unroll") for (int m = 0; m < 4; ++m) _Pragma("unroll") for (int k = 0; k < 2; ++k) dst[m][k] = *(const PG8_LAS bf16x8*)(lds + PG8_SA(b, h) + aoff + m * 2048 + k * 1024); } while (0)
; #define PG8_MMA(ai, bj, At, Bt) do { __builtin_amdgcn_s_setprio(1); _Pragma("unroll") for (int m = 0; m < 4; ++m) _Pragma("unroll") for (int n = 0; n < 2; ++n) _Pragma("unroll") for (int k = 0; k < 2; ++k) \
;         acc[ai][bj][m][n] = __builtin_amdgcn_mfma_f32_16x16x32_bf16(Bt[n][k], At[m][k], acc[ai][bj][m][n], 0, 0, 0); __builtin_amdgcn_s_setprio(0); } while (0)
; #define PG8_WAIT_V(n) asm volatile("s_waitcnt vmcnt(" #n ")" ::: "memory")
; #define PG8_WAIT_L(n) asm volatile("s_waitcnt lgkmcnt(" #n ")" ::: "memory")
; #define PG8_BAR __builtin_amdgcn_s_barrier()
; #define PG8_SCHED __builtin_amdgcn_sched_barrier(0)
; template <class Epi, class Sched, bool ALIGN_EPI = false, bool SP2 = false>
; __device__ __forceinline__ void gemm_phase(PG8_LAS unsigned char* lds, const Gemm g, const Sched& S, const Epi& E) {
;     ...
;         for (int t = 0; t < nt; t += 2) {
;     ...
;             PG8_LDA(At, 1, 1); PG8_STAGE(PG8_SB(1, 0), b3, voffB); PG8_STAGE(PG8_SB(1, 1), b3 + hstep, voffB); PG8_STAGE(PG8_SA(1, 0), a3, voffA);
;             PG8_WAIT_V(8); PG8_WAIT_L(0); PG8_BAR; PG8_MMA(1, 0, At, B0); PG8_MMA(1, 1, At, B1); PG8_BAR; PG8_SCHED;
	s_add_u32 s30, s30, s20
	s_addc_u32 s31, s31, 0
	s_add_i32 s29, s29, s77
	v_lshl_add_u64 v[214:215], s[30:31], 0, v[174:175]
	s_mov_b32 m0, s29
	ds_read_b128 v[160:163], v233 offset:49152
	ds_read_b128 v[210:213], v233 offset:50176
	ds_read_b128 v[218:221], v233 offset:51200
	ds_read_b128 v[234:237], v233 offset:52224
	ds_read_b128 v[238:241], v233 offset:53248
	ds_read_b128 v[242:245], v233 offset:54272
	ds_read_b128 v[246:249], v233 offset:55296
	ds_read_b128 v[250:253], v233 offset:56320
	global_load_lds_dwordx4 v[214:215], off
	s_add_i32 m0, s29, 0x2000
	v_lshl_add_u64 v[214:215], s[30:31], 0, v[176:177]
	s_add_u32 s30, s30, s21
	s_addc_u32 s31, s31, 0
	s_add_i32 s29, s50, s77
	global_load_lds_dwordx4 v[214:215], off
	v_lshl_add_u64 v[214:215], s[30:31], 0, v[174:175]
	s_mov_b32 m0, s29
	s_nop 0
	global_load_lds_dwordx4 v[214:215], off
	v_lshl_add_u64 v[214:215], s[30:31], 0, v[176:177]
	s_add_i32 m0, s29, 0x2000
	s_nop 0
	global_load_lds_dwordx4 v[214:215], off
	v_lshl_add_u64 v[214:215], s[12:13], 0, v[174:175]
	s_mov_b32 m0, s74
	s_nop 0
	global_load_lds_dwordx4 v[214:215], off
	v_lshl_add_u64 v[214:215], s[12:13], 0, v[176:177]
	s_mov_b32 m0, s75
	s_nop 0
	global_load_lds_dwordx4 v[214:215], off
	s_waitcnt vmcnt(8)
	s_waitcnt lgkmcnt(0)
	s_barrier
	v_mfma_f32_16x16x32_bf16 v[60:63], v[128:131], v[160:163], v[60:63]
	v_mfma_f32_16x16x32_bf16 v[52:55], v[136:139], v[160:163], v[52:55]
	v_mfma_f32_16x16x32_bf16 v[44:47], v[128:131], v[218:221], v[44:47]
	v_mfma_f32_16x16x32_bf16 v[36:39], v[136:139], v[218:221], v[36:39]
	v_mfma_f32_16x16x32_bf16 v[28:31], v[128:131], v[238:241], v[28:31]
	v_mfma_f32_16x16x32_bf16 v[20:23], v[136:139], v[238:241], v[20:23]
	v_mfma_f32_16x16x32_bf16 v[12:15], v[128:131], v[246:249], v[12:15]
	v_mfma_f32_16x16x32_bf16 v[4:7], v[136:139], v[246:249], v[4:7]
	v_mfma_f32_16x16x32_bf16 v[60:63], v[132:135], v[210:213], v[60:63]
	v_mfma_f32_16x16x32_bf16 v[52:55], v[140:143], v[210:213], v[52:55]
	v_mfma_f32_16x16x32_bf16 v[44:47], v[132:135], v[234:237], v[44:47]
	v_mfma_f32_16x16x32_bf16 v[36:39], v[140:143], v[234:237], v[36:39]
	v_mfma_f32_16x16x32_bf16 v[28:31], v[132:135], v[242:245], v[28:31]
	v_mfma_f32_16x16x32_bf16 v[20:23], v[140:143], v[242:245], v[20:23]
	v_mfma_f32_16x16x32_bf16 v[12:15], v[132:135], v[250:253], v[12:15]
	v_mfma_f32_16x16x32_bf16 v[4:7], v[140:143], v[250:253], v[4:7]
	v_mfma_f32_16x16x32_bf16 v[56:59], v[144:147], v[160:163], v[56:59]
	v_mfma_f32_16x16x32_bf16 v[48:51], v[152:155], v[160:163], v[48:51]
	v_mfma_f32_16x16x32_bf16 v[40:43], v[144:147], v[218:221], v[40:43]
	v_mfma_f32_16x16x32_bf16 v[32:35], v[152:155], v[218:221], v[32:35]
	v_mfma_f32_16x16x32_bf16 v[24:27], v[144:147], v[238:241], v[24:27]
	v_mfma_f32_16x16x32_bf16 v[16:19], v[152:155], v[238:241], v[16:19]
	v_mfma_f32_16x16x32_bf16 v[8:11], v[144:147], v[246:249], v[8:11]
	v_mfma_f32_16x16x32_bf16 v[0:3], v[152:155], v[246:249], v[0:3]
	v_mfma_f32_16x16x32_bf16 v[56:59], v[148:151], v[210:213], v[56:59]
	v_mfma_f32_16x16x32_bf16 v[48:51], v[156:159], v[210:213], v[48:51]
	v_mfma_f32_16x16x32_bf16 v[40:43], v[148:151], v[234:237], v[40:43]
	v_mfma_f32_16x16x32_bf16 v[32:35], v[156:159], v[234:237], v[32:35]
	v_mfma_f32_16x16x32_bf16 v[24:27], v[148:151], v[242:245], v[24:27]
	v_mfma_f32_16x16x32_bf16 v[16:19], v[156:159], v[242:245], v[16:19]
	v_mfma_f32_16x16x32_bf16 v[8:11], v[148:151], v[250:253], v[8:11]
	v_mfma_f32_16x16x32_bf16 v[0:3], v[156:159], v[250:253], v[0:3]
	s_barrier
	s_cmp_ge_u32 s14, s62
	s_mov_b64 s[12:13], s[14:15]
	s_cbranch_scc0 .LBB0_162
	s_setprio 0
	s_and_b64 vcc, exec, s[86:87]
	s_cbranch_vccz .LBB0_167
	s_barrier
	s_cmp_lt_i32 s58, 1
	s_mov_b64 s[8:9], -1
	s_cbranch_scc0 .LBB0_168
